# gMLP unit prologue (both layers): the 12 serialized W_s fragment loads for ks=2..7 hoisted next to the tile loads
# baseline (speedup 1.0000x reference)
; __device__ __forceinline__ unsigned cvt_pk_bf16(float lo, float hi) { unsigned r; asm volatile("v_cvt_pk_bf16_f32 %0, %1, %2" : "=v"(r) : "v"(lo), "v"(hi)); return r; }
; __device__ void gmlp_unit(const Ctx& c, int tid, int l, int ch, int g, unsigned short* T) {
;     ...
;     {
;         const int q = tid >> 4, c8 = (tid & 15) * 8;
;         u32x4 v[4];
; #pragma unroll
;         for (int ps = 0; ps < 4; ++ps) v[ps] = *(const u32x4*)(vn + (size_t)(q + 32 * ps) * 1024 + c8);
; #pragma unroll
;         for (int ps = 0; ps < 4; ++ps) { unsigned short* d = T + (q + 32 * ps) * 132 + c8; *(u32x2*)d = (u32x2){v[ps].x, v[ps].y}; *(u32x2*)(d + 4) = (u32x2){v[ps].z, v[ps].w}; }
;     }
;     bf16x8 af[8];
; #pragma unroll
;     for (int ks = 0; ks < 8; ++ks) { const f32x4 a0 = *(const f32x4*)(wsr + ks * 16), a1 = *(const f32x4*)(wsr + ks * 16 + 4);
;         u32x4 aw; aw.x = cvt_pk_bf16(a0[0], a0[1]); aw.y = cvt_pk_bf16(a0[2], a0[3]); aw.z = cvt_pk_bf16(a1[0], a1[1]); aw.w = cvt_pk_bf16(a1[2], a1[3]);
;         af[ks] = *reinterpret_cast<const bf16x8*>(&aw); }
;     __syncthreads();
;     f32x16 acc0 = {}, acc1 = {};
;     const unsigned short* tb = T + (hi * 8) * 132 + cb0 * 32 + r32;
; #pragma unroll
;     for (int ks = 0; ks < 8; ++ks) {
;         bf16x8 b0, b1;
; #pragma unroll
;         for (int j = 0; j < 8; ++j) { b0[j] = (short)tb[(ks * 16 + j) * 132]; b1[j] = (short)tb[(ks * 16 + j) * 132 + 32]; }
.LBB0_464:
	s_ashr_i32 s6, s35, 3
	s_lshl_b32 s16, s6, 7
	s_ashr_i32 s17, s16, 31
	s_and_b32 s4, s10, 0x380
	s_lshl_b64 s[16:17], s[16:17], 11
	s_add_u32 s7, s8, s16
	v_lshl_add_u64 v[0:1], v[32:33], 0, s[4:5]
	v_add_u32_e32 v86, s4, v44
	s_addc_u32 s15, s9, s17
	s_lshl_b32 s4, s4, 1
	s_add_u32 s16, s7, s4
	s_addc_u32 s17, s15, 0
	v_lshlrev_b64 v[0:1], 9, v[0:1]
	v_lshl_add_u64 v[8:9], s[16:17], 0, v[34:35]
	v_lshl_add_u64 v[24:25], v[78:79], 0, v[0:1]
	v_lshl_add_u64 v[26:27], v[8:9], 0, v[36:37]
	global_load_dwordx4 v[0:3], v[24:25], off offset:16
	global_load_dwordx4 v[4:7], v[24:25], off
	v_lshl_add_u64 v[28:29], v[8:9], 0, v[38:39]
	v_lshl_add_u64 v[30:31], v[8:9], 0, v[40:41]
	v_lshl_add_u64 v[84:85], v[8:9], 0, v[42:43]
	global_load_dwordx4 v[8:11], v[26:27], off
	global_load_dwordx4 v[12:15], v[28:29], off
	global_load_dwordx4 v[16:19], v[30:31], off
	global_load_dwordx4 v[20:23], v[84:85], off
	global_load_dwordx4 v[96:99], v[24:25], off offset:128
	global_load_dwordx4 v[198:201], v[24:25], off offset:144
	global_load_dwordx4 v[100:103], v[24:25], off offset:192
	global_load_dwordx4 v[202:205], v[24:25], off offset:208
	global_load_dwordx4 v[104:107], v[24:25], off offset:256
	global_load_dwordx4 v[206:209], v[24:25], off offset:272
	global_load_dwordx4 v[108:111], v[24:25], off offset:320
	global_load_dwordx4 v[210:213], v[24:25], off offset:336
	global_load_dwordx4 v[112:115], v[24:25], off offset:384
	global_load_dwordx4 v[218:221], v[24:25], off offset:400
	global_load_dwordx4 v[116:119], v[24:25], off offset:448
	global_load_dwordx4 v[222:225], v[24:25], off offset:464
	v_add_u32_e32 v91, 0x2100, v45
	v_add_u32_e32 v92, 0x4200, v45
	v_add_u32_e32 v93, 0x6300, v45
	s_ashr_i32 s7, s6, 31
	s_lshl_b64 s[6:7], s[6:7], 18
	s_add_u32 s6, s43, s6
	s_addc_u32 s7, s56, s7
	s_add_u32 s6, s6, s4
	v_mov_b32_e32 v81, v35
	s_addc_u32 s7, s7, 0
	v_mov_b32_e32 v83, v35
	v_lshl_add_u64 v[26:27], s[6:7], 0, v[80:81]
	v_lshl_add_u64 v[84:85], v[26:27], 0, v[82:83]
	v_ashrrev_i32_e32 v87, 31, v86
	v_lshl_add_u64 v[88:89], v[84:85], 0, v[46:47]
	s_add_i32 s35, s35, s38
	s_add_i32 s10, s10, s11
	s_cmpk_lt_i32 s35, 0x240
	s_waitcnt vmcnt(12)
	ds_write2_b64 v45, v[8:9], v[10:11] offset1:1
	ds_write2_b64 v91, v[12:13], v[14:15] offset1:1
	ds_write2_b64 v92, v[16:17], v[18:19] offset1:1
	ds_write2_b64 v93, v[20:21], v[22:23] offset1:1
	v_cvt_pk_bf16_f32 v4, v4, v5
	v_cvt_pk_bf16_f32 v5, v6, v7
	v_cvt_pk_bf16_f32 v6, v0, v1
	v_cvt_pk_bf16_f32 v7, v2, v3
	global_load_dwordx4 v[0:3], v[24:25], off offset:64
	global_load_dwordx4 v[8:11], v[24:25], off offset:80
	s_waitcnt vmcnt(1)
	v_cvt_pk_bf16_f32 v92, v0, v1
	v_cvt_pk_bf16_f32 v93, v2, v3
	s_waitcnt vmcnt(0)
	v_cvt_pk_bf16_f32 v94, v8, v9
	v_cvt_pk_bf16_f32 v95, v10, v11
	v_cvt_pk_bf16_f32 v96, v96, v97
	v_cvt_pk_bf16_f32 v97, v98, v99
	v_cvt_pk_bf16_f32 v98, v198, v199
	v_cvt_pk_bf16_f32 v99, v200, v201
	v_cvt_pk_bf16_f32 v100, v100, v101
	v_cvt_pk_bf16_f32 v101, v102, v103
	v_cvt_pk_bf16_f32 v102, v202, v203
	v_cvt_pk_bf16_f32 v103, v204, v205
	v_cvt_pk_bf16_f32 v104, v104, v105
	v_cvt_pk_bf16_f32 v105, v106, v107
	v_cvt_pk_bf16_f32 v106, v206, v207
	v_cvt_pk_bf16_f32 v107, v208, v209
	v_cvt_pk_bf16_f32 v108, v108, v109
	v_cvt_pk_bf16_f32 v109, v110, v111
	v_cvt_pk_bf16_f32 v110, v210, v211
	v_cvt_pk_bf16_f32 v111, v212, v213
	v_cvt_pk_bf16_f32 v112, v112, v113
	v_cvt_pk_bf16_f32 v113, v114, v115
	v_cvt_pk_bf16_f32 v114, v218, v219
	v_cvt_pk_bf16_f32 v115, v220, v221
	v_cvt_pk_bf16_f32 v116, v116, v117
	v_cvt_pk_bf16_f32 v117, v118, v119
	v_cvt_pk_bf16_f32 v118, v222, v223
	v_cvt_pk_bf16_f32 v119, v224, v225
	s_waitcnt lgkmcnt(0)
	s_barrier
	ds_read_u16 v0, v90
	ds_read_u16 v8, v90 offset:64
	ds_read_u16 v9, v90 offset:264
	ds_read_u16 v10, v90 offset:328
	ds_read_u16 v1, v90 offset:528
	ds_read_u16 v11, v90 offset:592
	ds_read_u16 v12, v90 offset:792
	ds_read_u16 v13, v90 offset:856
	ds_read_u16 v2, v90 offset:1056
	ds_read_u16 v14, v90 offset:1120
	ds_read_u16 v15, v90 offset:1320
	ds_read_u16 v81, v90 offset:1384
	ds_read_u16 v3, v90 offset:1584
	ds_read_u16 v83, v90 offset:1648
	ds_read_u16 v16, v90 offset:1848
	ds_read_u16 v91, v90 offset:1912
	ds_read_u16 v120, v90 offset:4224
	ds_read_u16 v124, v90 offset:4288
	ds_read_u16 v125, v90 offset:4488
	ds_read_u16 v126, v90 offset:4552
	ds_read_u16 v121, v90 offset:4752
	ds_read_u16 v127, v90 offset:4816
	ds_read_u16 v128, v90 offset:5016
	ds_read_u16 v129, v90 offset:5080
	ds_read_u16 v122, v90 offset:5280
	ds_read_u16 v130, v90 offset:5344
	ds_read_u16 v131, v90 offset:5544
	ds_read_u16 v132, v90 offset:5608
	ds_read_u16 v123, v90 offset:5808
	ds_read_u16 v133, v90 offset:5872
	ds_read_u16 v134, v90 offset:6072
	ds_read_u16 v135, v90 offset:6136
	ds_read_u16 v136, v90 offset:8448
	ds_read_u16 v137, v90 offset:8512
	ds_read_u16 v138, v90 offset:8712
	ds_read_u16 v139, v90 offset:8776
	ds_read_u16 v140, v90 offset:8976
	ds_read_u16 v141, v90 offset:9040
	ds_read_u16 v142, v90 offset:9240
	ds_read_u16 v143, v90 offset:9304
	ds_read_u16 v144, v90 offset:9504
	ds_read_u16 v145, v90 offset:9568
	ds_read_u16 v146, v90 offset:9768
	ds_read_u16 v147, v90 offset:9832
	ds_read_u16 v148, v90 offset:10032
	ds_read_u16 v149, v90 offset:10096
	ds_read_u16 v150, v90 offset:10296
	ds_read_u16 v151, v90 offset:10360
	ds_read_u16 v152, v90 offset:12672
	ds_read_u16 v153, v90 offset:12736
	ds_read_u16 v154, v90 offset:12936
	ds_read_u16 v155, v90 offset:13000
	ds_read_u16 v156, v90 offset:13200
	ds_read_u16 v157, v90 offset:13264
	ds_read_u16 v158, v90 offset:13464
	ds_read_u16 v159, v90 offset:13528
	ds_read_u16 v160, v90 offset:13728
	ds_read_u16 v161, v90 offset:13792
	ds_read_u16 v162, v90 offset:13992
	ds_read_u16 v163, v90 offset:14056
	ds_read_u16 v164, v90 offset:14256
	ds_read_u16 v165, v90 offset:14320
	ds_read_u16 v166, v90 offset:14520
	ds_read_u16 v167, v90 offset:14584
	ds_read_u16 v168, v90 offset:16896
	ds_read_u16 v169, v90 offset:16960
	ds_read_u16 v170, v90 offset:17160
	ds_read_u16 v171, v90 offset:17224
	ds_read_u16 v172, v90 offset:17424
	ds_read_u16 v173, v90 offset:17488
	ds_read_u16 v174, v90 offset:17688
	ds_read_u16 v175, v90 offset:17752
	ds_read_u16 v176, v90 offset:17952
	ds_read_u16 v177, v90 offset:18016
	ds_read_u16 v178, v90 offset:18216
	ds_read_u16 v179, v90 offset:18280
	ds_read_u16 v180, v90 offset:18480
	ds_read_u16 v181, v90 offset:18544
	ds_read_u16 v182, v90 offset:18744
	ds_read_u16 v183, v90 offset:18808
	ds_read_u16 v184, v90 offset:21120
	ds_read_u16 v185, v90 offset:21184
	ds_read_u16 v186, v90 offset:21384
	ds_read_u16 v187, v90 offset:21448
	ds_read_u16 v188, v90 offset:21648
	ds_read_u16 v189, v90 offset:21712
	ds_read_u16 v190, v90 offset:21912
	ds_read_u16 v191, v90 offset:21976
	ds_read_u16 v192, v90 offset:22176
	ds_read_u16 v193, v90 offset:22240
	s_waitcnt lgkmcnt(14)
; __device__ __forceinline__ float bf2f(bf16_t b) { return __uint_as_float(((unsigned)b) << 16); }
; __device__ __forceinline__ bf16_t f2bf(float f) { return (bf16_t)(cvt_pk_bf16(f, 0.f) & 0xffffu); }
; __device__ __forceinline__ int crow(int r, int hi) { return (r & 3) + 8 * (r >> 2) + 4 * hi; }
; __device__ void gmlp_unit(const Ctx& c, int tid, int l, int ch, int g, unsigned short* T) {
;     ...
; #pragma unroll
;     for (int ks = 0; ks < 8; ++ks) {
;         bf16x8 b0, b1;
; #pragma unroll
;         for (int j = 0; j < 8; ++j) { b0[j] = (short)tb[(ks * 16 + j) * 132]; b1[j] = (short)tb[(ks * 16 + j) * 132 + 32]; }
;         acc0 = __builtin_amdgcn_mfma_f32_32x32x16_bf16(af[ks], b0, acc0, 0, 0, 0);
;         acc1 = __builtin_amdgcn_mfma_f32_32x32x16_bf16(af[ks], b1, acc1, 0, 0, 0); }
; #pragma unroll
;     for (int r = 0; r < 16; ++r) { const int prow = pblk * 32 + att::crow(r, hi); const size_t t = (size_t)ch * 128 + prow;
;         const float bias = pk->in[11][(l * 8 + g) * 128 + prow];
;         bf16_t* up = AM0 + t * 1024 + g * 128 + cb0 * 32 + r32;
;         up[0] = f2bf(bf2f(up[0]) * (acc0[r] + bias)); up[32] = f2bf(bf2f(up[32]) * (acc1[r] + bias)); }
	v_perm_b32 v3, v16, v3, s14
	v_perm_b32 v2, v15, v2, s14
	v_perm_b32 v1, v12, v1, s14
	v_perm_b32 v0, v9, v0, s14
	v_perm_b32 v123, v134, v123, s14
	v_perm_b32 v122, v131, v122, s14
	v_mfma_f32_32x32x16_bf16 v[16:31], v[4:7], v[0:3], 0
	v_perm_b32 v3, v91, v83, s14
	v_perm_b32 v2, v81, v14, s14
	v_perm_b32 v1, v13, v11, s14
	v_perm_b32 v0, v10, v8, s14
	v_perm_b32 v121, v128, v121, s14
	v_perm_b32 v120, v125, v120, s14
	ds_read_u16 v194, v90 offset:22440
	ds_read_u16 v195, v90 offset:22504
	ds_read_u16 v196, v90 offset:22704
	v_mfma_f32_32x32x16_bf16 v[0:15], v[4:7], v[0:3], 0
	ds_read_u16 v81, v90 offset:22768
	ds_read_u16 v83, v90 offset:22968
	ds_read_u16 v91, v90 offset:23032
	ds_read_u16 v125, v90 offset:25344
	ds_read_u16 v128, v90 offset:25408
	ds_read_u16 v131, v90 offset:25608
	v_mfma_f32_32x32x16_bf16 v[16:31], v[92:95], v[120:123], v[16:31]
	v_perm_b32 v123, v135, v133, s14
	v_perm_b32 v122, v132, v130, s14
	v_perm_b32 v121, v129, v127, s14
	v_perm_b32 v120, v126, v124, s14
	s_nop 1
	v_mfma_f32_32x32x16_bf16 v[0:15], v[92:95], v[120:123], v[0:15]
	v_perm_b32 v95, v150, v148, s14
	v_perm_b32 v94, v146, v144, s14
	v_perm_b32 v93, v142, v140, s14
	v_perm_b32 v92, v138, v136, s14
	ds_read_u16 v120, v90 offset:25672
	ds_read_u16 v121, v90 offset:25872
	ds_read_u16 v122, v90 offset:25936
	ds_read_u16 v123, v90 offset:26136
	ds_read_u16 v124, v90 offset:26200
	ds_read_u16 v126, v90 offset:26400
	v_mfma_f32_32x32x16_bf16 v[16:31], v[96:99], v[92:95], v[16:31]
	v_perm_b32 v95, v151, v149, s14
	v_perm_b32 v94, v147, v145, s14
	v_perm_b32 v93, v143, v141, s14
	v_perm_b32 v92, v139, v137, s14
	s_nop 1
	v_mfma_f32_32x32x16_bf16 v[0:15], v[96:99], v[92:95], v[0:15]
	v_perm_b32 v95, v166, v164, s14
	v_perm_b32 v94, v162, v160, s14
	v_perm_b32 v93, v158, v156, s14
	v_perm_b32 v92, v154, v152, s14
	ds_read_u16 v96, v90 offset:26464
	ds_read_u16 v97, v90 offset:26664
	ds_read_u16 v98, v90 offset:26728
	ds_read_u16 v99, v90 offset:26928
	ds_read_u16 v127, v90 offset:26992
	ds_read_u16 v129, v90 offset:27192
	v_mfma_f32_32x32x16_bf16 v[16:31], v[100:103], v[92:95], v[16:31]
	v_perm_b32 v95, v167, v165, s14
	v_perm_b32 v94, v163, v161, s14
	v_perm_b32 v93, v159, v157, s14
	v_perm_b32 v92, v155, v153, s14
	s_nop 1
	v_mfma_f32_32x32x16_bf16 v[0:15], v[100:103], v[92:95], v[0:15]
	s_waitcnt lgkmcnt(14)
	v_perm_b32 v95, v182, v180, s14
	v_perm_b32 v94, v178, v176, s14
	v_perm_b32 v93, v174, v172, s14
	v_perm_b32 v92, v170, v168, s14
	ds_read_u16 v100, v90 offset:27256
	ds_read_u16 v101, v90 offset:29568
	ds_read_u16 v102, v90 offset:29632
	ds_read_u16 v103, v90 offset:29832
	ds_read_u16 v130, v90 offset:29896
	ds_read_u16 v132, v90 offset:30096
	v_mfma_f32_32x32x16_bf16 v[16:31], v[104:107], v[92:95], v[16:31]
	v_perm_b32 v95, v183, v181, s14
	v_perm_b32 v94, v179, v177, s14
	v_perm_b32 v93, v175, v173, s14
	v_perm_b32 v92, v171, v169, s14
	s_nop 1
	v_mfma_f32_32x32x16_bf16 v[0:15], v[104:107], v[92:95], v[0:15]
	ds_read_u16 v104, v90 offset:30160
	ds_read_u16 v105, v90 offset:30360
	ds_read_u16 v106, v90 offset:30424
	s_load_dwordx2 s[6:7], s[2:3], 0x58
	v_perm_b32 v95, v83, v196, s14
	v_perm_b32 v94, v194, v192, s14
	v_perm_b32 v93, v190, v188, s14
	v_perm_b32 v92, v186, v184, s14
	s_waitcnt lgkmcnt(0)
	v_lshl_add_u64 v[86:87], v[86:87], 2, s[6:7]
	global_load_ushort v83, v[88:89], off
	v_mfma_f32_32x32x16_bf16 v[16:31], v[108:111], v[92:95], v[16:31]
	v_perm_b32 v95, v91, v81, s14
	global_load_dword v81, v[86:87], off
	global_load_ushort v197, v[88:89], off offset:64
	v_lshl_add_u64 v[198:199], v[84:85], 0, v[48:49]
	global_load_ushort v230, v[198:199], off offset:64
	global_load_ushort v198, v[198:199], off
	global_load_dword v199, v[86:87], off offset:4
	v_lshl_add_u64 v[200:201], v[84:85], 0, v[50:51]
	global_load_ushort v231, v[200:201], off offset:64
	global_load_ushort v200, v[200:201], off
	global_load_dword v201, v[86:87], off offset:8
	v_lshl_add_u64 v[202:203], v[84:85], 0, v[52:53]
	global_load_ushort v232, v[202:203], off offset:64
	global_load_ushort v202, v[202:203], off
	global_load_dword v203, v[86:87], off offset:12
	v_lshl_add_u64 v[204:205], v[84:85], 0, v[54:55]
	global_load_ushort v233, v[204:205], off offset:64
	global_load_ushort v204, v[204:205], off
	global_load_dword v205, v[86:87], off offset:32
	v_lshl_add_u64 v[206:207], v[84:85], 0, v[56:57]
	global_load_ushort v234, v[206:207], off offset:64
	global_load_ushort v206, v[206:207], off
	global_load_dword v207, v[86:87], off offset:36
	v_lshl_add_u64 v[208:209], v[84:85], 0, v[58:59]
	global_load_ushort v235, v[208:209], off offset:64
	global_load_ushort v208, v[208:209], off
	global_load_dword v209, v[86:87], off offset:40
	v_lshl_add_u64 v[210:211], v[84:85], 0, v[60:61]
	global_load_ushort v236, v[210:211], off offset:64
	global_load_ushort v210, v[210:211], off
	global_load_dword v211, v[86:87], off offset:44
	v_lshl_add_u64 v[212:213], v[84:85], 0, v[62:63]
	global_load_ushort v237, v[212:213], off offset:64
	global_load_ushort v212, v[212:213], off
	global_load_dword v213, v[86:87], off offset:64
	v_lshl_add_u64 v[214:215], v[84:85], 0, v[64:65]
	global_load_ushort v238, v[214:215], off offset:64
	global_load_ushort v214, v[214:215], off
	global_load_dword v215, v[86:87], off offset:68
	v_lshl_add_u64 v[218:219], v[84:85], 0, v[66:67]
	global_load_ushort v239, v[218:219], off offset:64
	global_load_ushort v218, v[218:219], off
	global_load_dword v219, v[86:87], off offset:72
	v_lshl_add_u64 v[220:221], v[84:85], 0, v[68:69]
	global_load_ushort v240, v[220:221], off offset:64
	global_load_ushort v220, v[220:221], off
	global_load_dword v221, v[86:87], off offset:76
	v_lshl_add_u64 v[222:223], v[84:85], 0, v[70:71]
	global_load_ushort v241, v[222:223], off offset:64
	global_load_ushort v222, v[222:223], off
	global_load_dword v223, v[86:87], off offset:96
	v_lshl_add_u64 v[224:225], v[84:85], 0, v[72:73]
	global_load_ushort v242, v[224:225], off offset:64
	global_load_ushort v224, v[224:225], off
	global_load_dword v225, v[86:87], off offset:100
	v_lshl_add_u64 v[226:227], v[84:85], 0, v[74:75]
	global_load_ushort v243, v[226:227], off offset:64
	global_load_ushort v226, v[226:227], off
	global_load_dword v227, v[86:87], off offset:104
	v_lshl_add_u64 v[228:229], v[84:85], 0, v[76:77]
	global_load_ushort v244, v[228:229], off offset:64
	global_load_ushort v228, v[228:229], off
	global_load_dword v229, v[86:87], off offset:108
	v_perm_b32 v94, v195, v193, s14
	v_perm_b32 v93, v191, v189, s14
	v_perm_b32 v92, v187, v185, s14
	ds_read_u16 v91, v90 offset:30624
	ds_read_u16 v107, v90 offset:30688
	s_waitcnt vmcnt(47)
; __device__ void gmlp_unit(const Ctx& c, int tid, int l, int ch, int g, unsigned short* T) {
;     ...
; #pragma unroll
;     for (int ks = 0; ks < 8; ++ks) {
;         bf16x8 b0, b1;
; #pragma unroll
;         for (int j = 0; j < 8; ++j) { b0[j] = (short)tb[(ks * 16 + j) * 132]; b1[j] = (short)tb[(ks * 16 + j) * 132 + 32]; }
;         acc0 = __builtin_amdgcn_mfma_f32_32x32x16_bf16(af[ks], b0, acc0, 0, 0, 0);
;         acc1 = __builtin_amdgcn_mfma_f32_32x32x16_bf16(af[ks], b1, acc1, 0, 0, 0); }
	v_lshlrev_b32_e32 v83, 16, v83
	v_mfma_f32_32x32x16_bf16 v[0:15], v[108:111], v[92:95], v[0:15]
	v_perm_b32 v95, v129, v99, s14
	v_perm_b32 v94, v97, v126, s14
	v_perm_b32 v93, v123, v121, s14
	v_perm_b32 v92, v131, v125, s14
	ds_read_u16 v97, v90 offset:30888
	ds_read_u16 v99, v90 offset:31152
	ds_read_u16 v108, v90 offset:31416
	v_mfma_f32_32x32x16_bf16 v[16:31], v[112:115], v[92:95], v[16:31]
	v_perm_b32 v95, v100, v127, s14
	v_perm_b32 v94, v98, v96, s14
	v_perm_b32 v93, v124, v122, s14
	v_perm_b32 v92, v120, v128, s14
	ds_read_u16 v98, v90 offset:30952
	ds_read_u16 v100, v90 offset:31216
	ds_read_u16 v109, v90 offset:31480
	v_mfma_f32_32x32x16_bf16 v[0:15], v[112:115], v[92:95], v[0:15]
	s_waitcnt lgkmcnt(3)
	v_perm_b32 v95, v108, v99, s14
	v_perm_b32 v94, v97, v91, s14
	v_perm_b32 v93, v105, v132, s14
	v_perm_b32 v92, v103, v101, s14
	v_lshl_add_u64 v[96:97], v[84:85], 0, v[48:49]
	s_nop 0
	v_mfma_f32_32x32x16_bf16 v[16:31], v[116:119], v[92:95], v[16:31]
	s_waitcnt lgkmcnt(0)
	v_perm_b32 v95, v109, v100, s14
	v_perm_b32 v94, v98, v107, s14
	v_perm_b32 v93, v106, v104, s14
	v_perm_b32 v92, v130, v102, s14
	s_nop 1
	v_mfma_f32_32x32x16_bf16 v[0:15], v[116:119], v[92:95], v[0:15]
	s_waitcnt vmcnt(0)
; __device__ __forceinline__ float bf2f(bf16_t b) { return __uint_as_float(((unsigned)b) << 16); }
; __device__ __forceinline__ bf16_t f2bf(float f) { return (bf16_t)(cvt_pk_bf16(f, 0.f) & 0xffffu); }
; __device__ __forceinline__ int crow(int r, int hi) { return (r & 3) + 8 * (r >> 2) + 4 * hi; }
; __device__ void gmlp_unit(const Ctx& c, int tid, int l, int ch, int g, unsigned short* T) {
;     ...
;     for (int r = 0; r < 16; ++r) { const int prow = pblk * 32 + att::crow(r, hi); const size_t t = (size_t)ch * 128 + prow;
;         const float bias = pk->in[11][(l * 8 + g) * 128 + prow];
;         bf16_t* up = AM0 + t * 1024 + g * 128 + cb0 * 32 + r32;
;         up[0] = f2bf(bf2f(up[0]) * (acc0[r] + bias)); up[32] = f2bf(bf2f(up[32]) * (acc1[r] + bias)); }
	s_nop 2
	v_add_f32_e32 v16, v16, v81
	v_mul_f32_e32 v16, v16, v83
	v_cvt_pk_bf16_f32 v16, v16, v35
	v_mov_b32_e32 v83, v197
	s_nop 0
	global_store_short v[88:89], v16, off
	s_nop 2
	v_add_f32_e32 v0, v0, v81
	v_lshlrev_b32_e32 v16, 16, v83
	v_mul_f32_e32 v0, v0, v16
	v_cvt_pk_bf16_f32 v0, v0, v35
	v_mov_b32_e32 v16, v198
	v_mov_b32_e32 v81, v199
	v_add_f32_e32 v1, v1, v81
	global_store_short v[88:89], v0, off offset:64
	v_lshlrev_b32_e32 v0, 16, v16
	v_add_f32_e32 v16, v17, v81
	v_mul_f32_e32 v0, v16, v0
	v_cvt_pk_bf16_f32 v0, v0, v35
	v_mov_b32_e32 v83, v230
	v_lshl_add_u64 v[16:17], v[84:85], 0, v[50:51]
	global_store_short v[96:97], v0, off
	v_lshlrev_b32_e32 v0, 16, v83
	v_mul_f32_e32 v0, v1, v0
	v_cvt_pk_bf16_f32 v0, v0, v35
	v_mov_b32_e32 v1, v200
	v_mov_b32_e32 v81, v201
	v_add_f32_e32 v2, v2, v81
	global_store_short v[96:97], v0, off offset:64
	v_lshlrev_b32_e32 v0, 16, v1
	v_add_f32_e32 v1, v18, v81
	v_mul_f32_e32 v0, v1, v0
	v_cvt_pk_bf16_f32 v18, v0, v35
	v_mov_b32_e32 v83, v231
	v_lshl_add_u64 v[0:1], v[84:85], 0, v[52:53]
	global_store_short v[16:17], v18, off
	v_lshlrev_b32_e32 v18, 16, v83
	v_mul_f32_e32 v2, v2, v18
	v_cvt_pk_bf16_f32 v2, v2, v35
	v_mov_b32_e32 v18, v202
	v_mov_b32_e32 v81, v203
	v_add_f32_e32 v3, v3, v81
	global_store_short v[16:17], v2, off offset:64
	v_lshlrev_b32_e32 v2, 16, v18
	v_add_f32_e32 v16, v19, v81
	v_mul_f32_e32 v2, v16, v2
	v_cvt_pk_bf16_f32 v2, v2, v35
	v_mov_b32_e32 v18, v232
	v_lshl_add_u64 v[16:17], v[84:85], 0, v[54:55]
	global_store_short v[0:1], v2, off
	v_lshlrev_b32_e32 v2, 16, v18
	v_mul_f32_e32 v2, v3, v2
	v_cvt_pk_bf16_f32 v2, v2, v35
	v_mov_b32_e32 v3, v204
	v_mov_b32_e32 v18, v205
	v_add_f32_e32 v4, v4, v18
	global_store_short v[0:1], v2, off offset:64
	v_lshlrev_b32_e32 v0, 16, v3
	v_add_f32_e32 v1, v20, v18
	v_mul_f32_e32 v0, v1, v0
	v_cvt_pk_bf16_f32 v2, v0, v35
	v_mov_b32_e32 v3, v233
	v_lshl_add_u64 v[0:1], v[84:85], 0, v[56:57]
	global_store_short v[16:17], v2, off
	v_lshlrev_b32_e32 v2, 16, v3
	v_mul_f32_e32 v2, v4, v2
	v_cvt_pk_bf16_f32 v2, v2, v35
	v_mov_b32_e32 v3, v206
	v_mov_b32_e32 v4, v207
	s_nop 0
	global_store_short v[16:17], v2, off offset:64
	v_lshlrev_b32_e32 v2, 16, v3
	v_add_f32_e32 v3, v21, v4
	v_mul_f32_e32 v2, v3, v2
	v_cvt_pk_bf16_f32 v16, v2, v35
	v_mov_b32_e32 v17, v234
	v_add_f32_e32 v4, v5, v4
	v_lshl_add_u64 v[2:3], v[84:85], 0, v[58:59]
	global_store_short v[0:1], v16, off
	v_lshlrev_b32_e32 v5, 16, v17
	v_mul_f32_e32 v4, v4, v5
	v_cvt_pk_bf16_f32 v4, v4, v35
	v_mov_b32_e32 v5, v208
	v_mov_b32_e32 v16, v209
	v_add_f32_e32 v6, v6, v16
	global_store_short v[0:1], v4, off offset:64
	v_lshlrev_b32_e32 v0, 16, v5
	v_add_f32_e32 v1, v22, v16
	v_mul_f32_e32 v0, v1, v0
	v_cvt_pk_bf16_f32 v4, v0, v35
	v_mov_b32_e32 v5, v235
	v_lshl_add_u64 v[0:1], v[84:85], 0, v[60:61]
	global_store_short v[2:3], v4, off
	v_lshlrev_b32_e32 v4, 16, v5
	v_mul_f32_e32 v4, v6, v4
	v_cvt_pk_bf16_f32 v4, v4, v35
	v_mov_b32_e32 v5, v210
	v_mov_b32_e32 v6, v211
	s_nop 0
	global_store_short v[2:3], v4, off offset:64
	v_lshlrev_b32_e32 v2, 16, v5
	v_add_f32_e32 v3, v23, v6
	v_mul_f32_e32 v2, v3, v2
	v_cvt_pk_bf16_f32 v4, v2, v35
	v_mov_b32_e32 v5, v236
	v_add_f32_e32 v6, v7, v6
	global_store_short v[0:1], v4, off
	v_lshl_add_u64 v[2:3], v[84:85], 0, v[62:63]
	v_lshlrev_b32_e32 v4, 16, v5
	v_mul_f32_e32 v4, v6, v4
	v_cvt_pk_bf16_f32 v4, v4, v35
	v_mov_b32_e32 v5, v212
	v_mov_b32_e32 v6, v213
	s_nop 0
	global_store_short v[0:1], v4, off offset:64
	v_lshlrev_b32_e32 v0, 16, v5
	v_add_f32_e32 v1, v24, v6
	v_mul_f32_e32 v0, v1, v0
	v_cvt_pk_bf16_f32 v4, v0, v35
	v_mov_b32_e32 v5, v237
	v_add_f32_e32 v6, v8, v6
	global_store_short v[2:3], v4, off
	v_lshl_add_u64 v[0:1], v[84:85], 0, v[64:65]
	v_lshlrev_b32_e32 v4, 16, v5
	v_mul_f32_e32 v4, v6, v4
	v_cvt_pk_bf16_f32 v4, v4, v35
	v_mov_b32_e32 v5, v214
	v_mov_b32_e32 v6, v215
	s_nop 0
	global_store_short v[2:3], v4, off offset:64
	v_lshlrev_b32_e32 v2, 16, v5
	v_add_f32_e32 v3, v25, v6
	v_mul_f32_e32 v2, v3, v2
	v_cvt_pk_bf16_f32 v4, v2, v35
	v_mov_b32_e32 v5, v238
	v_add_f32_e32 v6, v9, v6
	global_store_short v[0:1], v4, off
	v_lshl_add_u64 v[2:3], v[84:85], 0, v[66:67]
	v_lshlrev_b32_e32 v4, 16, v5
	v_mul_f32_e32 v4, v6, v4
	v_cvt_pk_bf16_f32 v4, v4, v35
	v_mov_b32_e32 v5, v218
	v_mov_b32_e32 v6, v219
	s_nop 0
	global_store_short v[0:1], v4, off offset:64
	v_lshlrev_b32_e32 v0, 16, v5
	v_add_f32_e32 v1, v26, v6
	v_mul_f32_e32 v0, v1, v0
	v_cvt_pk_bf16_f32 v4, v0, v35
	v_mov_b32_e32 v5, v239
	v_add_f32_e32 v6, v10, v6
	global_store_short v[2:3], v4, off
	v_lshl_add_u64 v[0:1], v[84:85], 0, v[68:69]
	v_lshlrev_b32_e32 v4, 16, v5
	v_mul_f32_e32 v4, v6, v4
	v_cvt_pk_bf16_f32 v4, v4, v35
	v_mov_b32_e32 v5, v220
	v_mov_b32_e32 v6, v221
	s_nop 0
	global_store_short v[2:3], v4, off offset:64
	v_lshlrev_b32_e32 v2, 16, v5
	v_add_f32_e32 v3, v27, v6
	v_mul_f32_e32 v2, v3, v2
	v_cvt_pk_bf16_f32 v4, v2, v35
	v_mov_b32_e32 v5, v240
	v_add_f32_e32 v6, v11, v6
	global_store_short v[0:1], v4, off
	v_lshl_add_u64 v[2:3], v[84:85], 0, v[70:71]
	v_lshlrev_b32_e32 v4, 16, v5
	v_mul_f32_e32 v4, v6, v4
	v_cvt_pk_bf16_f32 v4, v4, v35
	v_mov_b32_e32 v5, v222
	v_mov_b32_e32 v6, v223
	s_nop 0
	global_store_short v[0:1], v4, off offset:64
	v_lshlrev_b32_e32 v0, 16, v5
	v_add_f32_e32 v1, v28, v6
	v_mul_f32_e32 v0, v1, v0
	v_cvt_pk_bf16_f32 v4, v0, v35
	v_mov_b32_e32 v5, v241
	v_add_f32_e32 v6, v12, v6
	global_store_short v[2:3], v4, off
	v_lshl_add_u64 v[0:1], v[84:85], 0, v[72:73]
	v_lshlrev_b32_e32 v4, 16, v5
	v_mul_f32_e32 v4, v6, v4
	v_cvt_pk_bf16_f32 v4, v4, v35
	v_mov_b32_e32 v5, v224
	v_mov_b32_e32 v6, v225
	s_nop 0
	global_store_short v[2:3], v4, off offset:64
	v_lshlrev_b32_e32 v2, 16, v5
	v_add_f32_e32 v3, v29, v6
	v_mul_f32_e32 v2, v3, v2
	v_cvt_pk_bf16_f32 v4, v2, v35
	v_mov_b32_e32 v5, v242
	v_add_f32_e32 v6, v13, v6
	global_store_short v[0:1], v4, off
	v_lshl_add_u64 v[2:3], v[84:85], 0, v[74:75]
	v_lshlrev_b32_e32 v4, 16, v5
	v_mul_f32_e32 v4, v6, v4
	v_cvt_pk_bf16_f32 v4, v4, v35
	v_mov_b32_e32 v5, v226
	v_mov_b32_e32 v6, v227
	s_nop 0
	global_store_short v[0:1], v4, off offset:64
	v_lshlrev_b32_e32 v0, 16, v5
	v_add_f32_e32 v1, v30, v6
	v_mul_f32_e32 v0, v1, v0
	v_cvt_pk_bf16_f32 v4, v0, v35
	v_mov_b32_e32 v5, v243
	v_add_f32_e32 v6, v14, v6
	global_store_short v[2:3], v4, off
	v_lshl_add_u64 v[0:1], v[84:85], 0, v[76:77]
	v_lshlrev_b32_e32 v4, 16, v5
	v_mul_f32_e32 v4, v6, v4
	v_cvt_pk_bf16_f32 v4, v4, v35
	v_mov_b32_e32 v5, v228
	v_mov_b32_e32 v6, v229
	s_nop 0
	global_store_short v[2:3], v4, off offset:64
	v_lshlrev_b32_e32 v2, 16, v5
	v_add_f32_e32 v3, v31, v6
	v_mul_f32_e32 v2, v3, v2
	v_cvt_pk_bf16_f32 v2, v2, v35
	v_mov_b32_e32 v3, v244
	v_add_f32_e32 v4, v15, v6
	global_store_short v[0:1], v2, off
	v_lshlrev_b32_e32 v2, 16, v3
	v_mul_f32_e32 v2, v4, v2
	v_cvt_pk_bf16_f32 v2, v2, v35
	global_store_short v[0:1], v2, off offset:64
	s_barrier
	s_cbranch_scc1 .LBB0_464

; __device__ __forceinline__ unsigned cvt_pk_bf16(float lo, float hi) { unsigned r; asm volatile("v_cvt_pk_bf16_f32 %0, %1, %2" : "=v"(r) : "v"(lo), "v"(hi)); return r; }
; __device__ void gmlp_unit(const Ctx& c, int tid, int l, int ch, int g, unsigned short* T) {
;     ...
;     {
;         const int q = tid >> 4, c8 = (tid & 15) * 8;
;         u32x4 v[4];
; #pragma unroll
;         for (int ps = 0; ps < 4; ++ps) v[ps] = *(const u32x4*)(vn + (size_t)(q + 32 * ps) * 1024 + c8);
; #pragma unroll
;         for (int ps = 0; ps < 4; ++ps) { unsigned short* d = T + (q + 32 * ps) * 132 + c8; *(u32x2*)d = (u32x2){v[ps].x, v[ps].y}; *(u32x2*)(d + 4) = (u32x2){v[ps].z, v[ps].w}; }
;     }
;     bf16x8 af[8];
; #pragma unroll
;     for (int ks = 0; ks < 8; ++ks) { const f32x4 a0 = *(const f32x4*)(wsr + ks * 16), a1 = *(const f32x4*)(wsr + ks * 16 + 4);
;         u32x4 aw; aw.x = cvt_pk_bf16(a0[0], a0[1]); aw.y = cvt_pk_bf16(a0[2], a0[3]); aw.z = cvt_pk_bf16(a1[0], a1[1]); aw.w = cvt_pk_bf16(a1[2], a1[3]);
;         af[ks] = *reinterpret_cast<const bf16x8*>(&aw); }
;     __syncthreads();
;     f32x16 acc0 = {}, acc1 = {};
;     const unsigned short* tb = T + (hi * 8) * 132 + cb0 * 32 + r32;
; #pragma unroll
;     for (int ks = 0; ks < 8; ++ks) {
;         bf16x8 b0, b1;
; #pragma unroll
;         for (int j = 0; j < 8; ++j) { b0[j] = (short)tb[(ks * 16 + j) * 132]; b1[j] = (short)tb[(ks * 16 + j) * 132 + 32]; }
.LBB0_1544:
	s_ashr_i32 s6, s35, 3
	s_lshl_b32 s16, s6, 7
	s_and_b32 s7, s10, 0x380
	s_ashr_i32 s17, s16, 31
	s_or_b32 s4, s7, 0x400
	s_lshl_b64 s[16:17], s[16:17], 11
	s_add_u32 s15, s8, s16
	s_addc_u32 s17, s9, s17
	s_lshl_b32 s18, s7, 1
	s_add_u32 s16, s15, s18
	v_lshl_add_u64 v[0:1], v[32:33], 0, s[4:5]
	s_addc_u32 s17, s17, 0
	v_lshlrev_b64 v[0:1], 9, v[0:1]
	v_lshl_add_u64 v[8:9], s[16:17], 0, v[34:35]
	v_lshl_add_u64 v[24:25], v[108:109], 0, v[0:1]
	v_lshl_add_u64 v[26:27], v[8:9], 0, v[36:37]
	global_load_dwordx4 v[0:3], v[24:25], off offset:16
	global_load_dwordx4 v[4:7], v[24:25], off
	v_lshl_add_u64 v[28:29], v[8:9], 0, v[38:39]
	v_lshl_add_u64 v[30:31], v[8:9], 0, v[40:41]
	v_lshl_add_u64 v[114:115], v[8:9], 0, v[42:43]
	global_load_dwordx4 v[8:11], v[26:27], off
	global_load_dwordx4 v[12:15], v[28:29], off
	global_load_dwordx4 v[16:19], v[30:31], off
	global_load_dwordx4 v[20:23], v[114:115], off
	global_load_dwordx4 v[126:129], v[24:25], off offset:128
	global_load_dwordx4 v[222:225], v[24:25], off offset:144
	global_load_dwordx4 v[130:133], v[24:25], off offset:192
	global_load_dwordx4 v[226:229], v[24:25], off offset:208
	global_load_dwordx4 v[134:137], v[24:25], off offset:256
	global_load_dwordx4 v[230:233], v[24:25], off offset:272
	global_load_dwordx4 v[138:141], v[24:25], off offset:320
	global_load_dwordx4 v[234:237], v[24:25], off offset:336
	global_load_dwordx4 v[142:145], v[24:25], off offset:384
	global_load_dwordx4 v[238:241], v[24:25], off offset:400
	global_load_dwordx4 v[146:149], v[24:25], off offset:448
	global_load_dwordx4 v[242:245], v[24:25], off offset:464
	v_add_u32_e32 v49, 0x2100, v45
	v_add_u32_e32 v53, 0x4200, v45
	v_add_u32_e32 v57, 0x6300, v45
	s_ashr_i32 s7, s6, 31
	s_lshl_b64 s[6:7], s[6:7], 18
	s_add_u32 s6, s50, s6
	s_addc_u32 s7, s51, s7
	s_add_u32 s6, s6, s18
	v_mov_b32_e32 v111, v35
	s_addc_u32 s7, s7, 0
	v_mov_b32_e32 v113, v35
	v_lshl_add_u64 v[26:27], s[6:7], 0, v[110:111]
	v_lshl_add_u64 v[114:115], v[26:27], 0, v[112:113]
	v_add_u32_e32 v118, s4, v44
	v_ashrrev_i32_e32 v119, 31, v118
	v_lshl_add_u64 v[116:117], v[114:115], 0, v[46:47]
	s_add_i32 s35, s35, s38
	s_add_i32 s10, s10, s11
	s_cmpk_lt_i32 s35, 0x200
	s_waitcnt vmcnt(12)
	ds_write2_b64 v45, v[8:9], v[10:11] offset1:1
	ds_write2_b64 v49, v[12:13], v[14:15] offset1:1
	ds_write2_b64 v53, v[16:17], v[18:19] offset1:1
	ds_write2_b64 v57, v[20:21], v[22:23] offset1:1
	v_cvt_pk_bf16_f32 v4, v4, v5
	v_cvt_pk_bf16_f32 v5, v6, v7
	v_cvt_pk_bf16_f32 v6, v0, v1
	v_cvt_pk_bf16_f32 v7, v2, v3
	global_load_dwordx4 v[0:3], v[24:25], off offset:64
	global_load_dwordx4 v[8:11], v[24:25], off offset:80
	s_waitcnt vmcnt(1)
	v_cvt_pk_bf16_f32 v122, v0, v1
	v_cvt_pk_bf16_f32 v123, v2, v3
	s_waitcnt vmcnt(0)
	v_cvt_pk_bf16_f32 v124, v8, v9
	v_cvt_pk_bf16_f32 v125, v10, v11
	v_cvt_pk_bf16_f32 v126, v126, v127
	v_cvt_pk_bf16_f32 v127, v128, v129
	v_cvt_pk_bf16_f32 v128, v222, v223
	v_cvt_pk_bf16_f32 v129, v224, v225
	v_cvt_pk_bf16_f32 v130, v130, v131
	v_cvt_pk_bf16_f32 v131, v132, v133
	v_cvt_pk_bf16_f32 v132, v226, v227
	v_cvt_pk_bf16_f32 v133, v228, v229
	v_cvt_pk_bf16_f32 v134, v134, v135
	v_cvt_pk_bf16_f32 v135, v136, v137
	v_cvt_pk_bf16_f32 v136, v230, v231
	v_cvt_pk_bf16_f32 v137, v232, v233
	v_cvt_pk_bf16_f32 v138, v138, v139
	v_cvt_pk_bf16_f32 v139, v140, v141
	v_cvt_pk_bf16_f32 v140, v234, v235
	v_cvt_pk_bf16_f32 v141, v236, v237
	v_cvt_pk_bf16_f32 v142, v142, v143
	v_cvt_pk_bf16_f32 v143, v144, v145
	v_cvt_pk_bf16_f32 v144, v238, v239
	v_cvt_pk_bf16_f32 v145, v240, v241
	v_cvt_pk_bf16_f32 v146, v146, v147
	v_cvt_pk_bf16_f32 v147, v148, v149
	v_cvt_pk_bf16_f32 v148, v242, v243
	v_cvt_pk_bf16_f32 v149, v244, v245
	s_waitcnt lgkmcnt(0)
	s_barrier
	ds_read_u16 v0, v120
	ds_read_u16 v8, v120 offset:64
	ds_read_u16 v9, v120 offset:264
	ds_read_u16 v10, v120 offset:328
	ds_read_u16 v1, v120 offset:528
	ds_read_u16 v11, v120 offset:592
	ds_read_u16 v12, v120 offset:792
	ds_read_u16 v13, v120 offset:856
	ds_read_u16 v2, v120 offset:1056
	ds_read_u16 v14, v120 offset:1120
	ds_read_u16 v15, v120 offset:1320
	ds_read_u16 v49, v120 offset:1384
	ds_read_u16 v3, v120 offset:1584
	ds_read_u16 v53, v120 offset:1648
	ds_read_u16 v16, v120 offset:1848
	ds_read_u16 v57, v120 offset:1912
	ds_read_u16 v61, v120 offset:4224
	ds_read_u16 v65, v120 offset:4288
	ds_read_u16 v69, v120 offset:4488
	ds_read_u16 v73, v120 offset:4552
	ds_read_u16 v77, v120 offset:4752
	ds_read_u16 v81, v120 offset:4816
	ds_read_u16 v85, v120 offset:5016
	ds_read_u16 v89, v120 offset:5080
	ds_read_u16 v93, v120 offset:5280
	ds_read_u16 v97, v120 offset:5344
	ds_read_u16 v101, v120 offset:5544
	ds_read_u16 v105, v120 offset:5608
	ds_read_u16 v111, v120 offset:5808
	ds_read_u16 v113, v120 offset:5872
	ds_read_u16 v121, v120 offset:6072
	ds_read_u16 v154, v120 offset:6136
	ds_read_u16 v155, v120 offset:8448
	ds_read_u16 v156, v120 offset:8512
	ds_read_u16 v157, v120 offset:8712
	ds_read_u16 v158, v120 offset:8776
	ds_read_u16 v159, v120 offset:8976
	ds_read_u16 v160, v120 offset:9040
	ds_read_u16 v161, v120 offset:9240
	ds_read_u16 v162, v120 offset:9304
	ds_read_u16 v163, v120 offset:9504
	ds_read_u16 v164, v120 offset:9568
	ds_read_u16 v165, v120 offset:9768
	ds_read_u16 v166, v120 offset:9832
	ds_read_u16 v167, v120 offset:10032
	ds_read_u16 v168, v120 offset:10096
	ds_read_u16 v169, v120 offset:10296
	ds_read_u16 v170, v120 offset:10360
	ds_read_u16 v171, v120 offset:12672
	ds_read_u16 v172, v120 offset:12736
	ds_read_u16 v173, v120 offset:12936
	ds_read_u16 v174, v120 offset:13000
	ds_read_u16 v175, v120 offset:13200
	ds_read_u16 v176, v120 offset:13264
	ds_read_u16 v177, v120 offset:13464
; __device__ __forceinline__ float bf2f(bf16_t b) { return __uint_as_float(((unsigned)b) << 16); }
; __device__ __forceinline__ bf16_t f2bf(float f) { return (bf16_t)(cvt_pk_bf16(f, 0.f) & 0xffffu); }
; __device__ __forceinline__ int crow(int r, int hi) { return (r & 3) + 8 * (r >> 2) + 4 * hi; }
; __device__ void gmlp_unit(const Ctx& c, int tid, int l, int ch, int g, unsigned short* T) {
;     ...
; #pragma unroll
;     for (int ks = 0; ks < 8; ++ks) {
;         bf16x8 b0, b1;
; #pragma unroll
;         for (int j = 0; j < 8; ++j) { b0[j] = (short)tb[(ks * 16 + j) * 132]; b1[j] = (short)tb[(ks * 16 + j) * 132 + 32]; }
;         acc0 = __builtin_amdgcn_mfma_f32_32x32x16_bf16(af[ks], b0, acc0, 0, 0, 0);
;         acc1 = __builtin_amdgcn_mfma_f32_32x32x16_bf16(af[ks], b1, acc1, 0, 0, 0); }
; #pragma unroll
;     for (int r = 0; r < 16; ++r) { const int prow = pblk * 32 + att::crow(r, hi); const size_t t = (size_t)ch * 128 + prow;
;         const float bias = pk->in[11][(l * 8 + g) * 128 + prow];
;         bf16_t* up = AM0 + t * 1024 + g * 128 + cb0 * 32 + r32;
;         up[0] = f2bf(bf2f(up[0]) * (acc0[r] + bias)); up[32] = f2bf(bf2f(up[32]) * (acc1[r] + bias)); }
	ds_read_u16 v178, v120 offset:13528
	ds_read_u16 v179, v120 offset:13728
	ds_read_u16 v180, v120 offset:13792
	ds_read_u16 v181, v120 offset:13992
	ds_read_u16 v182, v120 offset:14056
	ds_read_u16 v183, v120 offset:14256
	ds_read_u16 v184, v120 offset:14320
	ds_read_u16 v185, v120 offset:14520
	ds_read_u16 v186, v120 offset:14584
	ds_read_u16 v187, v120 offset:16896
	ds_read_u16 v188, v120 offset:16960
	ds_read_u16 v189, v120 offset:17160
	ds_read_u16 v190, v120 offset:17224
	ds_read_u16 v191, v120 offset:17424
	ds_read_u16 v192, v120 offset:17488
	ds_read_u16 v193, v120 offset:17688
	ds_read_u16 v194, v120 offset:17752
	ds_read_u16 v195, v120 offset:17952
	ds_read_u16 v196, v120 offset:18016
	ds_read_u16 v197, v120 offset:18216
	ds_read_u16 v198, v120 offset:18280
	ds_read_u16 v199, v120 offset:18480
	ds_read_u16 v200, v120 offset:18544
	ds_read_u16 v201, v120 offset:18744
	ds_read_u16 v202, v120 offset:18808
	ds_read_u16 v203, v120 offset:21120
	ds_read_u16 v204, v120 offset:21184
	ds_read_u16 v205, v120 offset:21384
	ds_read_u16 v206, v120 offset:21448
	ds_read_u16 v207, v120 offset:21648
	ds_read_u16 v208, v120 offset:21712
	ds_read_u16 v209, v120 offset:21912
	ds_read_u16 v210, v120 offset:21976
	ds_read_u16 v211, v120 offset:22176
	ds_read_u16 v212, v120 offset:22240
	ds_read_u16 v213, v120 offset:22440
	ds_read_u16 v214, v120 offset:22504
	ds_read_u16 v215, v120 offset:22704
	s_waitcnt lgkmcnt(14)
	v_perm_b32 v3, v16, v3, s14
	v_perm_b32 v2, v15, v2, s14
	v_perm_b32 v1, v12, v1, s14
	v_perm_b32 v0, v9, v0, s14
	v_perm_b32 v153, v121, v111, s14
	v_perm_b32 v152, v101, v93, s14
	v_mfma_f32_32x32x16_bf16 v[16:31], v[4:7], v[0:3], 0
	v_perm_b32 v3, v57, v53, s14
	v_perm_b32 v2, v49, v14, s14
	v_perm_b32 v1, v13, v11, s14
	v_perm_b32 v0, v10, v8, s14
	v_perm_b32 v151, v85, v77, s14
	v_perm_b32 v150, v69, v61, s14
	ds_read_u16 v218, v120 offset:22768
	ds_read_u16 v219, v120 offset:22968
	ds_read_u16 v220, v120 offset:23032
	v_mfma_f32_32x32x16_bf16 v[0:15], v[4:7], v[0:3], 0
	ds_read_u16 v49, v120 offset:25344
	ds_read_u16 v53, v120 offset:25408
	ds_read_u16 v57, v120 offset:25608
	ds_read_u16 v61, v120 offset:25672
	ds_read_u16 v69, v120 offset:25872
	ds_read_u16 v77, v120 offset:25936
	v_mfma_f32_32x32x16_bf16 v[16:31], v[122:125], v[150:153], v[16:31]
	v_perm_b32 v153, v154, v113, s14
	v_perm_b32 v152, v105, v97, s14
	v_perm_b32 v151, v89, v81, s14
	v_perm_b32 v150, v73, v65, s14
	ds_read_u16 v65, v120 offset:26136
	ds_read_u16 v73, v120 offset:26200
	ds_read_u16 v81, v120 offset:26400
	ds_read_u16 v85, v120 offset:26464
	ds_read_u16 v89, v120 offset:26664
	ds_read_u16 v93, v120 offset:26728
	ds_read_u16 v97, v120 offset:26928
	ds_read_u16 v101, v120 offset:26992
	ds_read_u16 v105, v120 offset:27192
	v_mfma_f32_32x32x16_bf16 v[0:15], v[122:125], v[150:153], v[0:15]
	v_perm_b32 v125, v169, v167, s14
	v_perm_b32 v124, v165, v163, s14
	v_perm_b32 v123, v161, v159, s14
	v_perm_b32 v122, v157, v155, s14
	ds_read_u16 v111, v120 offset:27256
	ds_read_u16 v113, v120 offset:29568
	ds_read_u16 v121, v120 offset:29632
	v_mfma_f32_32x32x16_bf16 v[16:31], v[126:129], v[122:125], v[16:31]
	v_perm_b32 v125, v170, v168, s14
	v_perm_b32 v124, v166, v164, s14
	v_perm_b32 v123, v162, v160, s14
	v_perm_b32 v122, v158, v156, s14
	s_nop 1
	v_mfma_f32_32x32x16_bf16 v[0:15], v[126:129], v[122:125], v[0:15]
	v_perm_b32 v125, v185, v183, s14
	v_perm_b32 v124, v181, v179, s14
	v_perm_b32 v123, v177, v175, s14
	v_perm_b32 v122, v173, v171, s14
	ds_read_u16 v126, v120 offset:29832
	ds_read_u16 v128, v120 offset:29896
	ds_read_u16 v127, v120 offset:30096
	v_mfma_f32_32x32x16_bf16 v[16:31], v[130:133], v[122:125], v[16:31]
	v_perm_b32 v125, v186, v184, s14
	v_perm_b32 v124, v182, v180, s14
	v_perm_b32 v123, v178, v176, s14
	v_perm_b32 v122, v174, v172, s14
	s_nop 1
	v_mfma_f32_32x32x16_bf16 v[0:15], v[130:133], v[122:125], v[0:15]
	ds_read_u16 v129, v120 offset:30160
	ds_read_u16 v130, v120 offset:30360
	ds_read_u16 v131, v120 offset:30424
	s_load_dwordx2 s[6:7], s[2:3], 0x58
	global_load_ushort v132, v[116:117], off
	v_perm_b32 v125, v201, v199, s14
	v_perm_b32 v124, v197, v195, s14
	v_perm_b32 v123, v193, v191, s14
	s_waitcnt lgkmcnt(0)
	v_lshl_add_u64 v[118:119], v[118:119], 2, s[6:7]
	global_load_dword v133, v[118:119], off
	global_load_ushort v221, v[116:117], off offset:64
	v_lshl_add_u64 v[222:223], v[114:115], 0, v[50:51]
	global_load_ushort v238, v[222:223], off offset:64
	global_load_ushort v222, v[222:223], off
	global_load_dword v223, v[118:119], off offset:4
	v_lshl_add_u64 v[224:225], v[114:115], 0, v[54:55]
	global_load_ushort v239, v[224:225], off offset:64
	global_load_ushort v224, v[224:225], off
	global_load_dword v225, v[118:119], off offset:8
	v_lshl_add_u64 v[226:227], v[114:115], 0, v[58:59]
	global_load_ushort v240, v[226:227], off offset:64
	global_load_ushort v226, v[226:227], off
	global_load_dword v227, v[118:119], off offset:12
	v_lshl_add_u64 v[228:229], v[114:115], 0, v[62:63]
	global_load_ushort v241, v[228:229], off offset:64
	global_load_ushort v228, v[228:229], off
	global_load_dword v229, v[118:119], off offset:32
	v_lshl_add_u64 v[230:231], v[114:115], 0, v[66:67]
	global_load_ushort v242, v[230:231], off offset:64
	global_load_ushort v230, v[230:231], off
	global_load_dword v231, v[118:119], off offset:36
	v_lshl_add_u64 v[232:233], v[114:115], 0, v[70:71]
	global_load_ushort v243, v[232:233], off offset:64
	global_load_ushort v232, v[232:233], off
	global_load_dword v233, v[118:119], off offset:40
	v_lshl_add_u64 v[234:235], v[114:115], 0, v[74:75]
	global_load_ushort v244, v[234:235], off offset:64
	global_load_ushort v234, v[234:235], off
	global_load_dword v235, v[118:119], off offset:44
	v_perm_b32 v122, v189, v187, s14
	s_nop 1
	v_mfma_f32_32x32x16_bf16 v[16:31], v[134:137], v[122:125], v[16:31]
	v_perm_b32 v125, v202, v200, s14
	v_perm_b32 v124, v198, v196, s14
	v_perm_b32 v123, v194, v192, s14
	v_perm_b32 v122, v190, v188, s14
	s_nop 1
	v_mfma_f32_32x32x16_bf16 v[0:15], v[134:137], v[122:125], v[0:15]
	v_perm_b32 v125, v219, v215, s14
	v_perm_b32 v124, v213, v211, s14
	v_perm_b32 v123, v209, v207, s14
	v_perm_b32 v122, v205, v203, s14
	ds_read_u16 v118, v120 offset:30624
	ds_read_u16 v134, v120 offset:30688
	ds_read_u16 v119, v120 offset:30888
	ds_read_u16 v135, v120 offset:31152
	ds_read_u16 v136, v120 offset:31416
	v_mfma_f32_32x32x16_bf16 v[16:31], v[138:141], v[122:125], v[16:31]
	v_perm_b32 v125, v220, v218, s14
	v_perm_b32 v124, v214, v212, s14
	v_perm_b32 v123, v210, v208, s14
	v_perm_b32 v122, v206, v204, s14
	s_nop 1
	v_mfma_f32_32x32x16_bf16 v[0:15], v[138:141], v[122:125], v[0:15]
	v_perm_b32 v125, v105, v97, s14
	v_perm_b32 v124, v89, v81, s14
	v_perm_b32 v123, v65, v69, s14
	v_perm_b32 v122, v57, v49, s14
	ds_read_u16 v49, v120 offset:30952
	ds_read_u16 v57, v120 offset:31216
	ds_read_u16 v65, v120 offset:31480
	s_waitcnt vmcnt(23)
; __device__ __forceinline__ float bf2f(bf16_t b) { return __uint_as_float(((unsigned)b) << 16); }
; __device__ __forceinline__ bf16_t f2bf(float f) { return (bf16_t)(cvt_pk_bf16(f, 0.f) & 0xffffu); }
; __device__ __forceinline__ int crow(int r, int hi) { return (r & 3) + 8 * (r >> 2) + 4 * hi; }
; __device__ void gmlp_unit(const Ctx& c, int tid, int l, int ch, int g, unsigned short* T) {
;     ...
;         acc0 = __builtin_amdgcn_mfma_f32_32x32x16_bf16(af[ks], b0, acc0, 0, 0, 0);
;         acc1 = __builtin_amdgcn_mfma_f32_32x32x16_bf16(af[ks], b1, acc1, 0, 0, 0); }
; #pragma unroll
;     for (int r = 0; r < 16; ++r) { const int prow = pblk * 32 + att::crow(r, hi); const size_t t = (size_t)ch * 128 + prow;
;         const float bias = pk->in[11][(l * 8 + g) * 128 + prow];
;         bf16_t* up = AM0 + t * 1024 + g * 128 + cb0 * 32 + r32;
;         up[0] = f2bf(bf2f(up[0]) * (acc0[r] + bias)); up[32] = f2bf(bf2f(up[32]) * (acc1[r] + bias)); }
	v_lshlrev_b32_e32 v69, 16, v132
	v_mfma_f32_32x32x16_bf16 v[16:31], v[142:145], v[122:125], v[16:31]
	s_waitcnt lgkmcnt(3)
	v_perm_b32 v125, v136, v135, s14
	v_perm_b32 v124, v119, v118, s14
	v_perm_b32 v123, v130, v127, s14
	v_perm_b32 v122, v126, v113, s14
	v_add_u32_e32 v118, s4, v48
	v_ashrrev_i32_e32 v119, 31, v118
	v_lshl_add_u64 v[126:127], v[114:115], 0, v[50:51]
	v_mfma_f32_32x32x16_bf16 v[16:31], v[146:149], v[122:125], v[16:31]
	v_perm_b32 v125, v111, v101, s14
	v_perm_b32 v124, v93, v85, s14
	v_perm_b32 v123, v73, v77, s14
	v_perm_b32 v122, v61, v53, s14
	v_lshl_add_u64 v[118:119], v[118:119], 2, s[6:7]
	s_waitcnt vmcnt(0)
	s_nop 5
	v_add_f32_e32 v16, v16, v133
	v_mul_f32_e32 v16, v16, v69
	v_cvt_pk_bf16_f32 v16, v16, v35
	v_mov_b32_e32 v69, v221
	v_mfma_f32_32x32x16_bf16 v[0:15], v[142:145], v[122:125], v[0:15]
	s_waitcnt lgkmcnt(0)
	v_perm_b32 v125, v65, v57, s14
	v_perm_b32 v124, v49, v134, s14
	v_perm_b32 v123, v131, v129, s14
	v_perm_b32 v122, v128, v121, s14
	global_store_short v[116:117], v16, off
	v_lshlrev_b32_e32 v16, 16, v69
	v_mfma_f32_32x32x16_bf16 v[0:15], v[146:149], v[122:125], v[0:15]
	s_nop 11
	v_add_f32_e32 v0, v0, v133
	v_mul_f32_e32 v0, v0, v16
	v_cvt_pk_bf16_f32 v0, v0, v35
	v_mov_b32_e32 v16, v222
	v_mov_b32_e32 v49, v223
	v_add_f32_e32 v1, v1, v49
	global_store_short v[116:117], v0, off offset:64
	v_lshlrev_b32_e32 v0, 16, v16
	v_add_f32_e32 v16, v17, v49
	v_mul_f32_e32 v0, v16, v0
	v_cvt_pk_bf16_f32 v0, v0, v35
	v_mov_b32_e32 v53, v238
	v_add_u32_e32 v16, s4, v52
	global_store_short v[126:127], v0, off
	v_ashrrev_i32_e32 v17, 31, v16
	v_lshl_add_u64 v[116:117], v[114:115], 0, v[54:55]
	v_lshl_add_u64 v[16:17], v[16:17], 2, s[6:7]
	v_lshlrev_b32_e32 v0, 16, v53
	v_mul_f32_e32 v0, v1, v0
	v_cvt_pk_bf16_f32 v0, v0, v35
	v_mov_b32_e32 v1, v224
	v_mov_b32_e32 v49, v225
	v_lshl_add_u64 v[16:17], v[114:115], 0, v[58:59]
	global_store_short v[126:127], v0, off offset:64
	v_lshlrev_b32_e32 v0, 16, v1
	v_add_f32_e32 v1, v18, v49
	v_mul_f32_e32 v0, v1, v0
	v_cvt_pk_bf16_f32 v18, v0, v35
	v_mov_b32_e32 v53, v239
	v_add_u32_e32 v0, s4, v56
	v_add_f32_e32 v2, v2, v49
	global_store_short v[116:117], v18, off
	v_ashrrev_i32_e32 v1, 31, v0
	v_lshl_add_u64 v[0:1], v[0:1], 2, s[6:7]
	v_lshlrev_b32_e32 v18, 16, v53
	v_mul_f32_e32 v2, v2, v18
	v_cvt_pk_bf16_f32 v2, v2, v35
	v_mov_b32_e32 v18, v226
	v_mov_b32_e32 v49, v227
	v_lshlrev_b32_e32 v0, 16, v18
	v_add_f32_e32 v1, v19, v49
	global_store_short v[116:117], v2, off offset:64
	v_mul_f32_e32 v0, v1, v0
	v_cvt_pk_bf16_f32 v2, v0, v35
	v_mov_b32_e32 v53, v240
	v_add_u32_e32 v0, s4, v60
	v_add_f32_e32 v3, v3, v49
	global_store_short v[16:17], v2, off
	v_ashrrev_i32_e32 v1, 31, v0
	v_lshl_add_u64 v[18:19], v[114:115], 0, v[62:63]
	v_lshl_add_u64 v[0:1], v[0:1], 2, s[6:7]
	v_lshlrev_b32_e32 v2, 16, v53
	v_mul_f32_e32 v2, v3, v2
	v_cvt_pk_bf16_f32 v2, v2, v35
	v_mov_b32_e32 v3, v228
	v_mov_b32_e32 v49, v229
	v_lshlrev_b32_e32 v0, 16, v3
	v_add_f32_e32 v1, v20, v49
	global_store_short v[16:17], v2, off offset:64
	v_mul_f32_e32 v0, v1, v0
	v_cvt_pk_bf16_f32 v16, v0, v35
	v_mov_b32_e32 v17, v241
	v_add_u32_e32 v0, s4, v64
	v_add_f32_e32 v4, v4, v49
	global_store_short v[18:19], v16, off
	v_ashrrev_i32_e32 v1, 31, v0
	v_lshl_add_u64 v[2:3], v[114:115], 0, v[66:67]
	v_lshl_add_u64 v[0:1], v[0:1], 2, s[6:7]
	v_lshlrev_b32_e32 v16, 16, v17
	v_mul_f32_e32 v4, v4, v16
	v_cvt_pk_bf16_f32 v4, v4, v35
	v_mov_b32_e32 v16, v230
	v_mov_b32_e32 v20, v231
	v_lshlrev_b32_e32 v0, 16, v16
	v_add_f32_e32 v1, v21, v20
	global_store_short v[18:19], v4, off offset:64
	v_mul_f32_e32 v0, v1, v0
	v_cvt_pk_bf16_f32 v4, v0, v35
	v_mov_b32_e32 v18, v242
	v_add_u32_e32 v0, s4, v68
	v_add_f32_e32 v5, v5, v20
	global_store_short v[2:3], v4, off
	v_ashrrev_i32_e32 v1, 31, v0
	v_lshl_add_u64 v[16:17], v[114:115], 0, v[70:71]
	v_lshl_add_u64 v[0:1], v[0:1], 2, s[6:7]
	v_lshlrev_b32_e32 v4, 16, v18
	v_mul_f32_e32 v4, v5, v4
	v_cvt_pk_bf16_f32 v4, v4, v35
	v_mov_b32_e32 v5, v232
	v_mov_b32_e32 v18, v233
	v_lshlrev_b32_e32 v0, 16, v5
	v_add_f32_e32 v1, v22, v18
	global_store_short v[2:3], v4, off offset:64
	v_mul_f32_e32 v0, v1, v0
	v_cvt_pk_bf16_f32 v4, v0, v35
	v_mov_b32_e32 v5, v243
	v_add_u32_e32 v0, s4, v72
	v_add_f32_e32 v6, v6, v18
	global_store_short v[16:17], v4, off
	v_ashrrev_i32_e32 v1, 31, v0
	v_lshl_add_u64 v[2:3], v[114:115], 0, v[74:75]
	v_lshl_add_u64 v[0:1], v[0:1], 2, s[6:7]
	v_lshlrev_b32_e32 v4, 16, v5
	v_mul_f32_e32 v4, v6, v4
	v_cvt_pk_bf16_f32 v4, v4, v35
	v_mov_b32_e32 v5, v234
	v_mov_b32_e32 v6, v235
	v_lshlrev_b32_e32 v0, 16, v5
	v_add_f32_e32 v1, v23, v6
	global_store_short v[16:17], v4, off offset:64
	v_mul_f32_e32 v0, v1, v0
	v_cvt_pk_bf16_f32 v16, v0, v35
	v_mov_b32_e32 v17, v244
	v_add_u32_e32 v0, s4, v76
	v_add_f32_e32 v6, v7, v6
	v_ashrrev_i32_e32 v1, 31, v0
	v_lshl_add_u64 v[4:5], v[114:115], 0, v[78:79]
	v_lshl_add_u64 v[0:1], v[0:1], 2, s[6:7]
	global_store_short v[2:3], v16, off
	v_lshlrev_b32_e32 v7, 16, v17
	v_mul_f32_e32 v6, v6, v7
	v_cvt_pk_bf16_f32 v6, v6, v35
	v_lshl_add_u64 v[222:223], v[114:115], 0, v[78:79]
	global_load_ushort v221, v[222:223], off offset:64
	global_load_ushort v222, v[222:223], off
	global_load_dword v223, v[0:1], off offset:0
	v_lshl_add_u64 v[224:225], v[114:115], 0, v[82:83]
	global_load_ushort v238, v[224:225], off offset:64
	global_load_ushort v224, v[224:225], off
	global_load_dword v225, v[0:1], off offset:4
	v_lshl_add_u64 v[226:227], v[114:115], 0, v[86:87]
	global_load_ushort v239, v[226:227], off offset:64
	global_load_ushort v226, v[226:227], off
	global_load_dword v227, v[0:1], off offset:8
	v_lshl_add_u64 v[228:229], v[114:115], 0, v[90:91]
	global_load_ushort v240, v[228:229], off offset:64
	global_load_ushort v228, v[228:229], off
	global_load_dword v229, v[0:1], off offset:12
	v_lshl_add_u64 v[230:231], v[114:115], 0, v[94:95]
	global_load_ushort v241, v[230:231], off offset:64
	global_load_ushort v230, v[230:231], off
	global_load_dword v231, v[0:1], off offset:32
	v_lshl_add_u64 v[232:233], v[114:115], 0, v[98:99]
	global_load_ushort v242, v[232:233], off offset:64
	global_load_ushort v232, v[232:233], off
	global_load_dword v233, v[0:1], off offset:36
	v_lshl_add_u64 v[234:235], v[114:115], 0, v[102:103]
	global_load_ushort v243, v[234:235], off offset:64
	global_load_ushort v234, v[234:235], off
	global_load_dword v235, v[0:1], off offset:40
	v_lshl_add_u64 v[236:237], v[114:115], 0, v[106:107]
	global_load_ushort v244, v[236:237], off offset:64
	global_load_ushort v236, v[236:237], off
	global_load_dword v237, v[0:1], off offset:44
	s_waitcnt vmcnt(0)
; __device__ __forceinline__ float bf2f(bf16_t b) { return __uint_as_float(((unsigned)b) << 16); }
; __device__ __forceinline__ bf16_t f2bf(float f) { return (bf16_t)(cvt_pk_bf16(f, 0.f) & 0xffffu); }
; __device__ __forceinline__ int crow(int r, int hi) { return (r & 3) + 8 * (r >> 2) + 4 * hi; }
; __device__ void gmlp_unit(const Ctx& c, int tid, int l, int ch, int g, unsigned short* T) {
;     ...
;     for (int r = 0; r < 16; ++r) { const int prow = pblk * 32 + att::crow(r, hi); const size_t t = (size_t)ch * 128 + prow;
;         const float bias = pk->in[11][(l * 8 + g) * 128 + prow];
;         bf16_t* up = AM0 + t * 1024 + g * 128 + cb0 * 32 + r32;
;         up[0] = f2bf(bf2f(up[0]) * (acc0[r] + bias)); up[32] = f2bf(bf2f(up[32]) * (acc1[r] + bias)); }
	v_mov_b32_e32 v7, v222
	v_mov_b32_e32 v16, v223
	v_lshlrev_b32_e32 v0, 16, v7
	v_add_f32_e32 v1, v24, v16
	global_store_short v[2:3], v6, off offset:64
	v_mul_f32_e32 v0, v1, v0
	v_cvt_pk_bf16_f32 v6, v0, v35
	v_mov_b32_e32 v7, v221
	v_add_u32_e32 v0, s4, v80
	v_add_f32_e32 v8, v8, v16
	global_store_short v[4:5], v6, off
	v_ashrrev_i32_e32 v1, 31, v0
	v_lshl_add_u64 v[2:3], v[114:115], 0, v[82:83]
	v_lshl_add_u64 v[0:1], v[0:1], 2, s[6:7]
	v_lshlrev_b32_e32 v6, 16, v7
	v_mul_f32_e32 v6, v8, v6
	v_cvt_pk_bf16_f32 v6, v6, v35
	v_mov_b32_e32 v7, v224
	v_mov_b32_e32 v8, v225
	v_lshlrev_b32_e32 v0, 16, v7
	v_add_f32_e32 v1, v25, v8
	global_store_short v[4:5], v6, off offset:64
	v_mul_f32_e32 v0, v1, v0
	v_cvt_pk_bf16_f32 v6, v0, v35
	v_mov_b32_e32 v7, v238
	v_add_u32_e32 v0, s4, v84
	v_add_f32_e32 v8, v9, v8
	global_store_short v[2:3], v6, off
	v_ashrrev_i32_e32 v1, 31, v0
	v_lshl_add_u64 v[4:5], v[114:115], 0, v[86:87]
	v_lshl_add_u64 v[0:1], v[0:1], 2, s[6:7]
	v_lshlrev_b32_e32 v6, 16, v7
	v_mul_f32_e32 v6, v8, v6
	v_cvt_pk_bf16_f32 v6, v6, v35
	v_mov_b32_e32 v7, v226
	v_mov_b32_e32 v8, v227
	v_lshlrev_b32_e32 v0, 16, v7
	v_add_f32_e32 v1, v26, v8
	global_store_short v[2:3], v6, off offset:64
	v_mul_f32_e32 v0, v1, v0
	v_cvt_pk_bf16_f32 v6, v0, v35
	v_mov_b32_e32 v7, v239
	v_add_u32_e32 v0, s4, v88
	v_add_f32_e32 v8, v10, v8
	global_store_short v[4:5], v6, off
	v_ashrrev_i32_e32 v1, 31, v0
	v_lshl_add_u64 v[2:3], v[114:115], 0, v[90:91]
	v_lshl_add_u64 v[0:1], v[0:1], 2, s[6:7]
	v_lshlrev_b32_e32 v6, 16, v7
	v_mul_f32_e32 v6, v8, v6
	v_cvt_pk_bf16_f32 v6, v6, v35
	v_mov_b32_e32 v7, v228
	v_mov_b32_e32 v8, v229
	v_lshlrev_b32_e32 v0, 16, v7
	v_add_f32_e32 v1, v27, v8
	global_store_short v[4:5], v6, off offset:64
	v_mul_f32_e32 v0, v1, v0
	v_cvt_pk_bf16_f32 v6, v0, v35
	v_mov_b32_e32 v7, v240
	v_add_u32_e32 v0, s4, v92
	v_add_f32_e32 v8, v11, v8
	global_store_short v[2:3], v6, off
	v_ashrrev_i32_e32 v1, 31, v0
	v_lshl_add_u64 v[4:5], v[114:115], 0, v[94:95]
	v_lshl_add_u64 v[0:1], v[0:1], 2, s[6:7]
	v_lshlrev_b32_e32 v6, 16, v7
	v_mul_f32_e32 v6, v8, v6
	v_cvt_pk_bf16_f32 v6, v6, v35
	v_mov_b32_e32 v7, v230
	v_mov_b32_e32 v8, v231
	v_lshlrev_b32_e32 v0, 16, v7
	v_add_f32_e32 v1, v28, v8
	global_store_short v[2:3], v6, off offset:64
	v_mul_f32_e32 v0, v1, v0
	v_cvt_pk_bf16_f32 v6, v0, v35
	v_mov_b32_e32 v7, v241
	v_add_u32_e32 v0, s4, v96
	v_add_f32_e32 v8, v12, v8
	global_store_short v[4:5], v6, off
	v_ashrrev_i32_e32 v1, 31, v0
	v_lshl_add_u64 v[2:3], v[114:115], 0, v[98:99]
	v_lshl_add_u64 v[0:1], v[0:1], 2, s[6:7]
	v_lshlrev_b32_e32 v6, 16, v7
	v_mul_f32_e32 v6, v8, v6
	v_cvt_pk_bf16_f32 v6, v6, v35
	v_mov_b32_e32 v7, v232
	v_mov_b32_e32 v8, v233
	v_lshlrev_b32_e32 v0, 16, v7
	v_add_f32_e32 v1, v29, v8
	global_store_short v[4:5], v6, off offset:64
	v_mul_f32_e32 v0, v1, v0
	v_cvt_pk_bf16_f32 v6, v0, v35
	v_mov_b32_e32 v7, v242
	v_add_u32_e32 v0, s4, v100
	v_add_f32_e32 v8, v13, v8
	global_store_short v[2:3], v6, off
	v_ashrrev_i32_e32 v1, 31, v0
	v_lshl_add_u64 v[4:5], v[114:115], 0, v[102:103]
	v_lshl_add_u64 v[0:1], v[0:1], 2, s[6:7]
	v_lshlrev_b32_e32 v6, 16, v7
	v_mul_f32_e32 v6, v8, v6
	v_cvt_pk_bf16_f32 v6, v6, v35
	v_mov_b32_e32 v7, v234
	v_mov_b32_e32 v8, v235
	v_lshlrev_b32_e32 v0, 16, v7
	v_add_f32_e32 v1, v30, v8
	global_store_short v[2:3], v6, off offset:64
	v_mul_f32_e32 v0, v1, v0
	v_cvt_pk_bf16_f32 v6, v0, v35
	v_mov_b32_e32 v7, v243
	v_add_u32_e32 v0, s4, v104
	v_add_f32_e32 v8, v14, v8
	global_store_short v[4:5], v6, off
	v_ashrrev_i32_e32 v1, 31, v0
	v_lshl_add_u64 v[2:3], v[114:115], 0, v[106:107]
	v_lshl_add_u64 v[0:1], v[0:1], 2, s[6:7]
	v_lshlrev_b32_e32 v6, 16, v7
	v_mul_f32_e32 v6, v8, v6
	v_cvt_pk_bf16_f32 v6, v6, v35
	v_mov_b32_e32 v7, v236
	v_mov_b32_e32 v8, v237
	v_lshlrev_b32_e32 v0, 16, v7
	v_add_f32_e32 v1, v31, v8
	v_mul_f32_e32 v0, v1, v0
	global_store_short v[4:5], v6, off offset:64
	v_cvt_pk_bf16_f32 v0, v0, v35
	v_mov_b32_e32 v1, v244
	v_add_f32_e32 v4, v15, v8
	global_store_short v[2:3], v0, off
	v_lshlrev_b32_e32 v0, 16, v1
	v_mul_f32_e32 v0, v4, v0
	v_cvt_pk_bf16_f32 v0, v0, v35
	global_store_short v[2:3], v0, off offset:64
	s_barrier
	s_cbranch_scc1 .LBB0_1544
